# v12 + removed the now-dead original twiddle setup before the 12 rewritten pair passes (liveness-checked)
# speedup vs baseline: 1.0357x; 1.0110x over previous
; DI float wave_sum(float v) { for (int o = 32; o > 0; o >>= 1) v += __shfl_xor(v, o); return v; }
;   const int lq2 = lq1 - 2, Q1 = 1 << lq1, Q2 = 1 << lq2; const float invM1 = 1.f / (float)(4 << lq1), invM2 = 1.f / (float)(4 << lq2);
;   for (int gg = tid; gg < NBT * (N / 16); gg += NTHR) { const int g = gg & (N / 16 - 1); float2* z = z0 + (gg / (N / 16)) * N; const int jp = g & (Q2 - 1), base = ((g >> lq2) << (lq2 + 4)) + jp; float2 x[4][4];
; #pragma unroll
;     for (int q1 = 0; q1 < 4; ++q1)
; #pragma unroll
;       for (int q2 = 0; q2 < 4; ++q2) x[q1][q2] = z[base + q1 * Q1 + q2 * Q2];
; #pragma unroll
;     for (int q2 = 0; q2 < 4; ++q2) bfly_fwd(x[0][q2], x[1][q2], x[2][q2], x[3][q2], (float)(jp + q2 * Q2) * invM1, x[0][q2], x[1][q2], x[2][q2], x[3][q2]);
; template <int LOGN> DI void filtfft_item(const Params& p, int ch, int cc, const float* kr, float2* kh) {
;     ...
;   ss = wave_sum(ss); if ((tid & 63) == 0) redbuf[tid >> 6] = ss;
;   __syncthreads();
;   float tot = 0.f;
; #pragma unroll
;   for (int w = 0; w < 8; ++w) tot += redbuf[w];
;   const float nrm = rsqrtf(tot + EPS) * (1.f / N), bias = p.hy_bias[ch * 256 + cc] * (1.f / N);
;   fft_fwd<LOGN, true>(z, tid);
.LBB0_1488:
	s_or_b64 exec, exec, s[0:1]
	s_add_i32 s0, 16, 0x20000
	v_mov_b32_e32 v0, s0
	v_readlane_b32 s0, v240, 48
	s_or_b32 s96, s21, s75
	s_waitcnt lgkmcnt(0)
	s_barrier
	ds_read_b128 v[6:9], v0
	v_mov_b32_e32 v0, s0
	s_lshl_b64 s[0:1], s[96:97], 2
	s_add_u32 s0, s18, s0
	s_addc_u32 s1, s19, s1
	ds_read_b128 v[2:5], v0
	global_load_dword v0, v1, s[0:1]
	s_movk_i32 s0, 0x200
	v_cmp_gt_i32_e32 vcc, s0, v10
	v_lshlrev_b32_e32 v11, 7, v10
	s_and_saveexec_b64 s[0:1], vcc
	s_cbranch_execz .LBB0_1491
	s_movk_i32 s8, 0x100
	v_and_b32_e32 v13, 0x8000, v11
	v_lshlrev_b32_sdwa v16, v151, v10 dst_sel:DWORD dst_unused:UNUSED_PAD src0_sel:DWORD src1_sel:BYTE_0
	v_add3_u32 v72, 16, v13, v16
	s_movk_i32 s8, 0x200
	s_movk_i32 s8, 0x300
	s_mov_b64 s[10:11], 0
	v_mov_b32_e32 v73, v10
	v_and_b32_e32 v241, 0xff, v73
	v_add_u32_e32 v250, 0x0, v241
	v_cvt_f32_u32_e32 v250, v250
	v_mul_f32_e32 v250, 0x39800000, v250
	v_cos_f32_e32 v218, v250
	v_sin_f32_e32 v219, v250
	s_nop 1
	v_xor_b32_e32 v219, 0x80000000, v219
	s_nop 0
	v_pk_mul_f32 v[126:127], v[218:219], v[218:219] op_sel:[1,1] op_sel_hi:[1,0]
	s_nop 0
	v_pk_fma_f32 v[220:221], v[218:219], v[218:219], v[126:127] op_sel_hi:[0,1,1] neg_lo:[0,0,1]
	s_nop 0
	v_pk_mul_f32 v[126:127], v[220:221], v[218:219] op_sel:[1,1] op_sel_hi:[1,0]
	s_nop 0
	v_pk_fma_f32 v[222:223], v[220:221], v[218:219], v[126:127] op_sel_hi:[0,1,1] neg_lo:[0,0,1]
	s_nop 0
	v_add_u32_e32 v250, 0x100, v241
	v_cvt_f32_u32_e32 v250, v250
	v_mul_f32_e32 v250, 0x39800000, v250
	v_cos_f32_e32 v224, v250
	v_sin_f32_e32 v225, v250
	s_nop 1
	v_xor_b32_e32 v225, 0x80000000, v225
	s_nop 0
	v_pk_mul_f32 v[126:127], v[224:225], v[224:225] op_sel:[1,1] op_sel_hi:[1,0]
	s_nop 0
	v_pk_fma_f32 v[226:227], v[224:225], v[224:225], v[126:127] op_sel_hi:[0,1,1] neg_lo:[0,0,1]
	s_nop 0
	v_pk_mul_f32 v[126:127], v[226:227], v[224:225] op_sel:[1,1] op_sel_hi:[1,0]
	s_nop 0
	v_pk_fma_f32 v[228:229], v[226:227], v[224:225], v[126:127] op_sel_hi:[0,1,1] neg_lo:[0,0,1]
	s_nop 0
	v_add_u32_e32 v250, 0x200, v241
	v_cvt_f32_u32_e32 v250, v250
	v_mul_f32_e32 v250, 0x39800000, v250
	v_cos_f32_e32 v230, v250
	v_sin_f32_e32 v231, v250
	s_nop 1
	v_xor_b32_e32 v231, 0x80000000, v231
	s_nop 0
	v_pk_mul_f32 v[126:127], v[230:231], v[230:231] op_sel:[1,1] op_sel_hi:[1,0]
	s_nop 0
	v_pk_fma_f32 v[232:233], v[230:231], v[230:231], v[126:127] op_sel_hi:[0,1,1] neg_lo:[0,0,1]
	s_nop 0
	v_pk_mul_f32 v[126:127], v[232:233], v[230:231] op_sel:[1,1] op_sel_hi:[1,0]
	s_nop 0
	v_pk_fma_f32 v[234:235], v[232:233], v[230:231], v[126:127] op_sel_hi:[0,1,1] neg_lo:[0,0,1]
	s_nop 0
	v_add_u32_e32 v250, 0x300, v241
	v_cvt_f32_u32_e32 v250, v250
	v_mul_f32_e32 v250, 0x39800000, v250
	v_cos_f32_e32 v236, v250
	v_sin_f32_e32 v237, v250
	s_nop 1
	v_xor_b32_e32 v237, 0x80000000, v237
	s_nop 0
	v_pk_mul_f32 v[126:127], v[236:237], v[236:237] op_sel:[1,1] op_sel_hi:[1,0]
	s_nop 0
	v_pk_fma_f32 v[238:239], v[236:237], v[236:237], v[126:127] op_sel_hi:[0,1,1] neg_lo:[0,0,1]
	s_nop 0
	v_pk_mul_f32 v[126:127], v[238:239], v[236:237] op_sel:[1,1] op_sel_hi:[1,0]
	s_nop 0
	v_pk_fma_f32 v[242:243], v[238:239], v[236:237], v[126:127] op_sel_hi:[0,1,1] neg_lo:[0,0,1]
	s_nop 0
	v_cvt_f32_u32_e32 v250, v241
	v_mul_f32_e32 v250, 0x3a800000, v250
	v_cos_f32_e32 v244, v250
	v_sin_f32_e32 v245, v250
	s_nop 1
	v_xor_b32_e32 v245, 0x80000000, v245
	s_nop 0
	v_pk_mul_f32 v[126:127], v[244:245], v[244:245] op_sel:[1,1] op_sel_hi:[1,0]
	s_nop 0
	v_pk_fma_f32 v[246:247], v[244:245], v[244:245], v[126:127] op_sel_hi:[0,1,1] neg_lo:[0,0,1]
	s_nop 0
	v_pk_mul_f32 v[126:127], v[246:247], v[244:245] op_sel:[1,1] op_sel_hi:[1,0]
	s_nop 0
	v_pk_fma_f32 v[248:249], v[246:247], v[244:245], v[126:127] op_sel_hi:[0,1,1] neg_lo:[0,0,1]
	s_nop 0

; DI float2 twid(float r) { return float2{__builtin_amdgcn_cosf(r), -__builtin_amdgcn_sinf(r)}; }
; DI void bfly_fwd(float2 a0, float2 a1, float2 a2, float2 a3, float r, float2& o0, float2& o1, float2& o2, float2& o3) {
;   float2 t0 = {a0.x + a2.x, a0.y + a2.y}, t1 = {a0.x - a2.x, a0.y - a2.y}, t2 = {a1.x + a3.x, a1.y + a3.y}, t3 = {a1.x - a3.x, a1.y - a3.y};
;   float2 b0 = {t0.x + t2.x, t0.y + t2.y}, b2 = {t0.x - t2.x, t0.y - t2.y}, b1 = {t1.x + t3.y, t1.y - t3.x}, b3 = {t1.x - t3.y, t1.y + t3.x};
;   float2 w1 = twid(r), w2 = cmul(w1, w1), w3 = cmul(w2, w1);
;   const int lq2 = lq1 - 2, Q1 = 1 << lq1, Q2 = 1 << lq2; const float invM1 = 1.f / (float)(4 << lq1), invM2 = 1.f / (float)(4 << lq2);
;   for (int gg = tid; gg < NBT * (N / 16); gg += NTHR) { const int g = gg & (N / 16 - 1); float2* z = z0 + (gg / (N / 16)) * N; const int jp = g & (Q2 - 1), base = ((g >> lq2) << (lq2 + 4)) + jp; float2 x[4][4];
; #pragma unroll
;     for (int q1 = 0; q1 < 4; ++q1)
; #pragma unroll
;       for (int q2 = 0; q2 < 4; ++q2) x[q1][q2] = z[base + q1 * Q1 + q2 * Q2];
; #pragma unroll
;     for (int q2 = 0; q2 < 4; ++q2) bfly_fwd(x[0][q2], x[1][q2], x[2][q2], x[3][q2], (float)(jp + q2 * Q2) * invM1, x[0][q2], x[1][q2], x[2][q2], x[3][q2]);
.LBB0_1491:
	s_or_b64 exec, exec, s[0:1]
	s_waitcnt lgkmcnt(0)
	s_barrier
	s_and_saveexec_b64 s[0:1], vcc
	s_cbranch_execz .LBB0_1494
	v_and_b32_e32 v13, 15, v10
	v_and_b32_e32 v11, 0xf800, v11
	v_lshlrev_b32_e32 v16, 3, v13
	v_add3_u32 v11, 16, v11, v16
	s_mov_b64 s[8:9], 0
	v_mov_b32_e32 v72, v10
	v_and_b32_e32 v241, 0xf, v72
	v_add_u32_e32 v250, 0x0, v241
	v_cvt_f32_u32_e32 v250, v250
	v_mul_f32_e32 v250, 0x3b800000, v250
	v_cos_f32_e32 v218, v250
	v_sin_f32_e32 v219, v250
	s_nop 1
	v_xor_b32_e32 v219, 0x80000000, v219
	s_nop 0
	v_pk_mul_f32 v[124:125], v[218:219], v[218:219] op_sel:[1,1] op_sel_hi:[1,0]
	s_nop 0
	v_pk_fma_f32 v[220:221], v[218:219], v[218:219], v[124:125] op_sel_hi:[0,1,1] neg_lo:[0,0,1]
	s_nop 0
	v_pk_mul_f32 v[124:125], v[220:221], v[218:219] op_sel:[1,1] op_sel_hi:[1,0]
	s_nop 0
	v_pk_fma_f32 v[222:223], v[220:221], v[218:219], v[124:125] op_sel_hi:[0,1,1] neg_lo:[0,0,1]
	s_nop 0
	v_add_u32_e32 v250, 0x10, v241
	v_cvt_f32_u32_e32 v250, v250
	v_mul_f32_e32 v250, 0x3b800000, v250
	v_cos_f32_e32 v224, v250
	v_sin_f32_e32 v225, v250
	s_nop 1
	v_xor_b32_e32 v225, 0x80000000, v225
	s_nop 0
	v_pk_mul_f32 v[124:125], v[224:225], v[224:225] op_sel:[1,1] op_sel_hi:[1,0]
	s_nop 0
	v_pk_fma_f32 v[226:227], v[224:225], v[224:225], v[124:125] op_sel_hi:[0,1,1] neg_lo:[0,0,1]
	s_nop 0
	v_pk_mul_f32 v[124:125], v[226:227], v[224:225] op_sel:[1,1] op_sel_hi:[1,0]
	s_nop 0
	v_pk_fma_f32 v[228:229], v[226:227], v[224:225], v[124:125] op_sel_hi:[0,1,1] neg_lo:[0,0,1]
	s_nop 0
	v_add_u32_e32 v250, 0x20, v241
	v_cvt_f32_u32_e32 v250, v250
	v_mul_f32_e32 v250, 0x3b800000, v250
	v_cos_f32_e32 v230, v250
	v_sin_f32_e32 v231, v250
	s_nop 1
	v_xor_b32_e32 v231, 0x80000000, v231
	s_nop 0
	v_pk_mul_f32 v[124:125], v[230:231], v[230:231] op_sel:[1,1] op_sel_hi:[1,0]
	s_nop 0
	v_pk_fma_f32 v[232:233], v[230:231], v[230:231], v[124:125] op_sel_hi:[0,1,1] neg_lo:[0,0,1]
	s_nop 0
	v_pk_mul_f32 v[124:125], v[232:233], v[230:231] op_sel:[1,1] op_sel_hi:[1,0]
	s_nop 0
	v_pk_fma_f32 v[234:235], v[232:233], v[230:231], v[124:125] op_sel_hi:[0,1,1] neg_lo:[0,0,1]
	s_nop 0
	v_add_u32_e32 v250, 0x30, v241
	v_cvt_f32_u32_e32 v250, v250
	v_mul_f32_e32 v250, 0x3b800000, v250
	v_cos_f32_e32 v236, v250
	v_sin_f32_e32 v237, v250
	s_nop 1
	v_xor_b32_e32 v237, 0x80000000, v237
	s_nop 0
	v_pk_mul_f32 v[124:125], v[236:237], v[236:237] op_sel:[1,1] op_sel_hi:[1,0]
	s_nop 0
	v_pk_fma_f32 v[238:239], v[236:237], v[236:237], v[124:125] op_sel_hi:[0,1,1] neg_lo:[0,0,1]
	s_nop 0
	v_pk_mul_f32 v[124:125], v[238:239], v[236:237] op_sel:[1,1] op_sel_hi:[1,0]
	s_nop 0
	v_pk_fma_f32 v[242:243], v[238:239], v[236:237], v[124:125] op_sel_hi:[0,1,1] neg_lo:[0,0,1]
	s_nop 0
	v_cvt_f32_u32_e32 v250, v241
	v_mul_f32_e32 v250, 0x3c800000, v250
	v_cos_f32_e32 v244, v250
	v_sin_f32_e32 v245, v250
	s_nop 1
	v_xor_b32_e32 v245, 0x80000000, v245
	s_nop 0
	v_pk_mul_f32 v[124:125], v[244:245], v[244:245] op_sel:[1,1] op_sel_hi:[1,0]
	s_nop 0
	v_pk_fma_f32 v[246:247], v[244:245], v[244:245], v[124:125] op_sel_hi:[0,1,1] neg_lo:[0,0,1]
	s_nop 0
	v_pk_mul_f32 v[124:125], v[246:247], v[244:245] op_sel:[1,1] op_sel_hi:[1,0]
	s_nop 0
	v_pk_fma_f32 v[248:249], v[246:247], v[244:245], v[124:125] op_sel_hi:[0,1,1] neg_lo:[0,0,1]
	s_nop 0

; DI float wave_sum(float v) { for (int o = 32; o > 0; o >>= 1) v += __shfl_xor(v, o); return v; }
;   const int lq2 = lq1 - 2, Q1 = 1 << lq1, Q2 = 1 << lq2; const float invM1 = 1.f / (float)(4 << lq1), invM2 = 1.f / (float)(4 << lq2);
;   for (int gg = tid; gg < NBT * (N / 16); gg += NTHR) { const int g = gg & (N / 16 - 1); float2* z = z0 + (gg / (N / 16)) * N; const int jp = g & (Q2 - 1), base = ((g >> lq2) << (lq2 + 4)) + jp; float2 x[4][4];
; #pragma unroll
;     for (int q1 = 0; q1 < 4; ++q1)
; #pragma unroll
;       for (int q2 = 0; q2 < 4; ++q2) x[q1][q2] = z[base + q1 * Q1 + q2 * Q2];
; #pragma unroll
;     for (int q2 = 0; q2 < 4; ++q2) bfly_fwd(x[0][q2], x[1][q2], x[2][q2], x[3][q2], (float)(jp + q2 * Q2) * invM1, x[0][q2], x[1][q2], x[2][q2], x[3][q2]);
; template <int LOGN> DI void filtfft_item(const Params& p, int ch, int cc, const float* kr, float2* kh) {
;     ...
;   ss = wave_sum(ss); if ((tid & 63) == 0) redbuf[tid >> 6] = ss;
;   __syncthreads();
;   float tot = 0.f;
; #pragma unroll
;   for (int w = 0; w < 8; ++w) tot += redbuf[w];
;   const float nrm = rsqrtf(tot + EPS) * (1.f / N), bias = p.hy_bias[ch * 256 + cc] * (1.f / N);
;   fft_fwd<LOGN, true>(z, tid);
.LBB0_1516:
	s_or_b64 exec, exec, s[0:1]
	s_add_i32 s0, 16, 0x20000
	v_mov_b32_e32 v0, s0
	v_readlane_b32 s0, v240, 48
	s_or_b32 s96, s21, s75
	s_waitcnt lgkmcnt(0)
	s_barrier
	ds_read_b128 v[6:9], v0
	v_mov_b32_e32 v0, s0
	s_lshl_b64 s[0:1], s[96:97], 2
	s_add_u32 s0, s18, s0
	s_addc_u32 s1, s19, s1
	ds_read_b128 v[2:5], v0
	global_load_dword v0, v1, s[0:1]
	s_movk_i32 s0, 0x400
	v_cmp_gt_i32_e32 vcc, s0, v10
	v_lshlrev_b32_e32 v11, 4, v10
	s_and_saveexec_b64 s[0:1], vcc
	s_cbranch_execz .LBB0_1519
	s_movk_i32 s10, 0x100
	s_movk_i32 s10, 0x200
	s_movk_i32 s10, 0x300
	v_lshlrev_b32_e32 v72, 4, v10
	s_mov_b64 s[12:13], 0
	v_mov_b32_e32 v73, v10
	v_and_b32_e32 v241, 0xff, v73
	v_add_u32_e32 v250, 0x0, v241
	v_cvt_f32_u32_e32 v250, v250
	v_mul_f32_e32 v250, 0x39800000, v250
	v_cos_f32_e32 v218, v250
	v_sin_f32_e32 v219, v250
	s_nop 1
	v_xor_b32_e32 v219, 0x80000000, v219
	s_nop 0
	v_pk_mul_f32 v[128:129], v[218:219], v[218:219] op_sel:[1,1] op_sel_hi:[1,0]
	s_nop 0
	v_pk_fma_f32 v[220:221], v[218:219], v[218:219], v[128:129] op_sel_hi:[0,1,1] neg_lo:[0,0,1]
	s_nop 0
	v_pk_mul_f32 v[128:129], v[220:221], v[218:219] op_sel:[1,1] op_sel_hi:[1,0]
	s_nop 0
	v_pk_fma_f32 v[222:223], v[220:221], v[218:219], v[128:129] op_sel_hi:[0,1,1] neg_lo:[0,0,1]
	s_nop 0
	v_add_u32_e32 v250, 0x100, v241
	v_cvt_f32_u32_e32 v250, v250
	v_mul_f32_e32 v250, 0x39800000, v250
	v_cos_f32_e32 v224, v250
	v_sin_f32_e32 v225, v250
	s_nop 1
	v_xor_b32_e32 v225, 0x80000000, v225
	s_nop 0
	v_pk_mul_f32 v[128:129], v[224:225], v[224:225] op_sel:[1,1] op_sel_hi:[1,0]
	s_nop 0
	v_pk_fma_f32 v[226:227], v[224:225], v[224:225], v[128:129] op_sel_hi:[0,1,1] neg_lo:[0,0,1]
	s_nop 0
	v_pk_mul_f32 v[128:129], v[226:227], v[224:225] op_sel:[1,1] op_sel_hi:[1,0]
	s_nop 0
	v_pk_fma_f32 v[228:229], v[226:227], v[224:225], v[128:129] op_sel_hi:[0,1,1] neg_lo:[0,0,1]
	s_nop 0
	v_add_u32_e32 v250, 0x200, v241
	v_cvt_f32_u32_e32 v250, v250
	v_mul_f32_e32 v250, 0x39800000, v250
	v_cos_f32_e32 v230, v250
	v_sin_f32_e32 v231, v250
	s_nop 1
	v_xor_b32_e32 v231, 0x80000000, v231
	s_nop 0
	v_pk_mul_f32 v[128:129], v[230:231], v[230:231] op_sel:[1,1] op_sel_hi:[1,0]
	s_nop 0
	v_pk_fma_f32 v[232:233], v[230:231], v[230:231], v[128:129] op_sel_hi:[0,1,1] neg_lo:[0,0,1]
	s_nop 0
	v_pk_mul_f32 v[128:129], v[232:233], v[230:231] op_sel:[1,1] op_sel_hi:[1,0]
	s_nop 0
	v_pk_fma_f32 v[234:235], v[232:233], v[230:231], v[128:129] op_sel_hi:[0,1,1] neg_lo:[0,0,1]
	s_nop 0
	v_add_u32_e32 v250, 0x300, v241
	v_cvt_f32_u32_e32 v250, v250
	v_mul_f32_e32 v250, 0x39800000, v250
	v_cos_f32_e32 v236, v250
	v_sin_f32_e32 v237, v250
	s_nop 1
	v_xor_b32_e32 v237, 0x80000000, v237
	s_nop 0
	v_pk_mul_f32 v[128:129], v[236:237], v[236:237] op_sel:[1,1] op_sel_hi:[1,0]
	s_nop 0
	v_pk_fma_f32 v[238:239], v[236:237], v[236:237], v[128:129] op_sel_hi:[0,1,1] neg_lo:[0,0,1]
	s_nop 0
	v_pk_mul_f32 v[128:129], v[238:239], v[236:237] op_sel:[1,1] op_sel_hi:[1,0]
	s_nop 0
	v_pk_fma_f32 v[242:243], v[238:239], v[236:237], v[128:129] op_sel_hi:[0,1,1] neg_lo:[0,0,1]
	s_nop 0
	v_cvt_f32_u32_e32 v250, v241
	v_mul_f32_e32 v250, 0x3a800000, v250
	v_cos_f32_e32 v244, v250
	v_sin_f32_e32 v245, v250
	s_nop 1
	v_xor_b32_e32 v245, 0x80000000, v245
	s_nop 0
	v_pk_mul_f32 v[128:129], v[244:245], v[244:245] op_sel:[1,1] op_sel_hi:[1,0]
	s_nop 0
	v_pk_fma_f32 v[246:247], v[244:245], v[244:245], v[128:129] op_sel_hi:[0,1,1] neg_lo:[0,0,1]
	s_nop 0
	v_pk_mul_f32 v[128:129], v[246:247], v[244:245] op_sel:[1,1] op_sel_hi:[1,0]
	s_nop 0
	v_pk_fma_f32 v[248:249], v[246:247], v[244:245], v[128:129] op_sel_hi:[0,1,1] neg_lo:[0,0,1]
	s_nop 0

; DI float2 twid(float r) { return float2{__builtin_amdgcn_cosf(r), -__builtin_amdgcn_sinf(r)}; }
; DI void bfly_fwd(float2 a0, float2 a1, float2 a2, float2 a3, float r, float2& o0, float2& o1, float2& o2, float2& o3) {
;   float2 t0 = {a0.x + a2.x, a0.y + a2.y}, t1 = {a0.x - a2.x, a0.y - a2.y}, t2 = {a1.x + a3.x, a1.y + a3.y}, t3 = {a1.x - a3.x, a1.y - a3.y};
;   float2 b0 = {t0.x + t2.x, t0.y + t2.y}, b2 = {t0.x - t2.x, t0.y - t2.y}, b1 = {t1.x + t3.y, t1.y - t3.x}, b3 = {t1.x - t3.y, t1.y + t3.x};
;   float2 w1 = twid(r), w2 = cmul(w1, w1), w3 = cmul(w2, w1);
;   const int lq2 = lq1 - 2, Q1 = 1 << lq1, Q2 = 1 << lq2; const float invM1 = 1.f / (float)(4 << lq1), invM2 = 1.f / (float)(4 << lq2);
;   for (int gg = tid; gg < NBT * (N / 16); gg += NTHR) { const int g = gg & (N / 16 - 1); float2* z = z0 + (gg / (N / 16)) * N; const int jp = g & (Q2 - 1), base = ((g >> lq2) << (lq2 + 4)) + jp; float2 x[4][4];
; #pragma unroll
;     for (int q1 = 0; q1 < 4; ++q1)
; #pragma unroll
;       for (int q2 = 0; q2 < 4; ++q2) x[q1][q2] = z[base + q1 * Q1 + q2 * Q2];
; #pragma unroll
;     for (int q2 = 0; q2 < 4; ++q2) bfly_fwd(x[0][q2], x[1][q2], x[2][q2], x[3][q2], (float)(jp + q2 * Q2) * invM1, x[0][q2], x[1][q2], x[2][q2], x[3][q2]);
.LBB0_1519:
	s_or_b64 exec, exec, s[0:1]
	s_waitcnt lgkmcnt(0)
	s_barrier
	s_and_saveexec_b64 s[0:1], vcc
	s_cbranch_execz .LBB0_1522
	v_and_b32_e32 v72, 15, v10
	s_mov_b64 s[10:11], 0
	v_mov_b32_e32 v73, v10
	v_and_b32_e32 v241, 0xf, v73
	v_add_u32_e32 v250, 0x0, v241
	v_cvt_f32_u32_e32 v250, v250
	v_mul_f32_e32 v250, 0x3b800000, v250
	v_cos_f32_e32 v218, v250
	v_sin_f32_e32 v219, v250
	s_nop 1
	v_xor_b32_e32 v219, 0x80000000, v219
	s_nop 0
	v_pk_mul_f32 v[128:129], v[218:219], v[218:219] op_sel:[1,1] op_sel_hi:[1,0]
	s_nop 0
	v_pk_fma_f32 v[220:221], v[218:219], v[218:219], v[128:129] op_sel_hi:[0,1,1] neg_lo:[0,0,1]
	s_nop 0
	v_pk_mul_f32 v[128:129], v[220:221], v[218:219] op_sel:[1,1] op_sel_hi:[1,0]
	s_nop 0
	v_pk_fma_f32 v[222:223], v[220:221], v[218:219], v[128:129] op_sel_hi:[0,1,1] neg_lo:[0,0,1]
	s_nop 0
	v_add_u32_e32 v250, 0x10, v241
	v_cvt_f32_u32_e32 v250, v250
	v_mul_f32_e32 v250, 0x3b800000, v250
	v_cos_f32_e32 v224, v250
	v_sin_f32_e32 v225, v250
	s_nop 1
	v_xor_b32_e32 v225, 0x80000000, v225
	s_nop 0
	v_pk_mul_f32 v[128:129], v[224:225], v[224:225] op_sel:[1,1] op_sel_hi:[1,0]
	s_nop 0
	v_pk_fma_f32 v[226:227], v[224:225], v[224:225], v[128:129] op_sel_hi:[0,1,1] neg_lo:[0,0,1]
	s_nop 0
	v_pk_mul_f32 v[128:129], v[226:227], v[224:225] op_sel:[1,1] op_sel_hi:[1,0]
	s_nop 0
	v_pk_fma_f32 v[228:229], v[226:227], v[224:225], v[128:129] op_sel_hi:[0,1,1] neg_lo:[0,0,1]
	s_nop 0
	v_add_u32_e32 v250, 0x20, v241
	v_cvt_f32_u32_e32 v250, v250
	v_mul_f32_e32 v250, 0x3b800000, v250
	v_cos_f32_e32 v230, v250
	v_sin_f32_e32 v231, v250
	s_nop 1
	v_xor_b32_e32 v231, 0x80000000, v231
	s_nop 0
	v_pk_mul_f32 v[128:129], v[230:231], v[230:231] op_sel:[1,1] op_sel_hi:[1,0]
	s_nop 0
	v_pk_fma_f32 v[232:233], v[230:231], v[230:231], v[128:129] op_sel_hi:[0,1,1] neg_lo:[0,0,1]
	s_nop 0
	v_pk_mul_f32 v[128:129], v[232:233], v[230:231] op_sel:[1,1] op_sel_hi:[1,0]
	s_nop 0
	v_pk_fma_f32 v[234:235], v[232:233], v[230:231], v[128:129] op_sel_hi:[0,1,1] neg_lo:[0,0,1]
	s_nop 0
	v_add_u32_e32 v250, 0x30, v241
	v_cvt_f32_u32_e32 v250, v250
	v_mul_f32_e32 v250, 0x3b800000, v250
	v_cos_f32_e32 v236, v250
	v_sin_f32_e32 v237, v250
	s_nop 1
	v_xor_b32_e32 v237, 0x80000000, v237
	s_nop 0
	v_pk_mul_f32 v[128:129], v[236:237], v[236:237] op_sel:[1,1] op_sel_hi:[1,0]
	s_nop 0
	v_pk_fma_f32 v[238:239], v[236:237], v[236:237], v[128:129] op_sel_hi:[0,1,1] neg_lo:[0,0,1]
	s_nop 0
	v_pk_mul_f32 v[128:129], v[238:239], v[236:237] op_sel:[1,1] op_sel_hi:[1,0]
	s_nop 0
	v_pk_fma_f32 v[242:243], v[238:239], v[236:237], v[128:129] op_sel_hi:[0,1,1] neg_lo:[0,0,1]
	s_nop 0
	v_cvt_f32_u32_e32 v250, v241
	v_mul_f32_e32 v250, 0x3c800000, v250
	v_cos_f32_e32 v244, v250
	v_sin_f32_e32 v245, v250
	s_nop 1
	v_xor_b32_e32 v245, 0x80000000, v245
	s_nop 0
	v_pk_mul_f32 v[128:129], v[244:245], v[244:245] op_sel:[1,1] op_sel_hi:[1,0]
	s_nop 0
	v_pk_fma_f32 v[246:247], v[244:245], v[244:245], v[128:129] op_sel_hi:[0,1,1] neg_lo:[0,0,1]
	s_nop 0
	v_pk_mul_f32 v[128:129], v[246:247], v[244:245] op_sel:[1,1] op_sel_hi:[1,0]
	s_nop 0
	v_pk_fma_f32 v[248:249], v[246:247], v[244:245], v[128:129] op_sel_hi:[0,1,1] neg_lo:[0,0,1]
	s_nop 0

; DI float2 twid(float r) { return float2{__builtin_amdgcn_cosf(r), -__builtin_amdgcn_sinf(r)}; }
; DI void bfly_fwd(float2 a0, float2 a1, float2 a2, float2 a3, float r, float2& o0, float2& o1, float2& o2, float2& o3) {
;   float2 t0 = {a0.x + a2.x, a0.y + a2.y}, t1 = {a0.x - a2.x, a0.y - a2.y}, t2 = {a1.x + a3.x, a1.y + a3.y}, t3 = {a1.x - a3.x, a1.y - a3.y};
;   float2 b0 = {t0.x + t2.x, t0.y + t2.y}, b2 = {t0.x - t2.x, t0.y - t2.y}, b1 = {t1.x + t3.y, t1.y - t3.x}, b3 = {t1.x - t3.y, t1.y + t3.x};
;   float2 w1 = twid(r), w2 = cmul(w1, w1), w3 = cmul(w2, w1);
;   const int lq2 = lq1 - 2, Q1 = 1 << lq1, Q2 = 1 << lq2; const float invM1 = 1.f / (float)(4 << lq1), invM2 = 1.f / (float)(4 << lq2);
;   for (int gg = tid; gg < NBT * (N / 16); gg += NTHR) { const int g = gg & (N / 16 - 1); float2* z = z0 + (gg / (N / 16)) * N; const int jp = g & (Q2 - 1), base = ((g >> lq2) << (lq2 + 4)) + jp; float2 x[4][4];
; #pragma unroll
;     for (int q1 = 0; q1 < 4; ++q1)
; #pragma unroll
;       for (int q2 = 0; q2 < 4; ++q2) x[q1][q2] = z[base + q1 * Q1 + q2 * Q2];
; #pragma unroll
;     for (int q2 = 0; q2 < 4; ++q2) bfly_fwd(x[0][q2], x[1][q2], x[2][q2], x[3][q2], (float)(jp + q2 * Q2) * invM1, x[0][q2], x[1][q2], x[2][q2], x[3][q2]);
.LBB0_1598:
	s_or_b64 exec, exec, s[0:1]
	s_movk_i32 s0, 0x400
	v_cmp_gt_i32_e32 vcc, s0, v75
	s_movk_i32 s0, 0x100
	v_or_b32_sdwa v77, v75, s0 dst_sel:DWORD dst_unused:UNUSED_PAD src0_sel:BYTE_0 src1_sel:DWORD
	s_movk_i32 s0, 0x200
	v_lshlrev_b32_e32 v62, 7, v75
	v_cvt_f32_ubyte0_e32 v2, v75
	v_or_b32_sdwa v76, v75, s0 dst_sel:DWORD dst_unused:UNUSED_PAD src0_sel:BYTE_0 src1_sel:DWORD
	s_movk_i32 s0, 0x300
	v_and_b32_e32 v79, 0x8000, v62
	v_lshlrev_b32_sdwa v80, v151, v75 dst_sel:DWORD dst_unused:UNUSED_PAD src0_sel:DWORD src1_sel:BYTE_0
	v_mul_f32_e32 v78, 0x39800000, v2
	v_or_b32_sdwa v0, v75, s0 dst_sel:DWORD dst_unused:UNUSED_PAD src0_sel:BYTE_0 src1_sel:DWORD
	v_mul_f32_e32 v81, 0x3a800000, v2
	s_waitcnt lgkmcnt(0)
	s_barrier
	s_and_saveexec_b64 s[0:1], vcc
	s_cbranch_execz .LBB0_1601
	v_add3_u32 v63, 16, v79, v80
	s_mov_b64 s[80:81], 0
	v_mov_b32_e32 v64, v75
	v_and_b32_e32 v241, 0xff, v64
	v_add_u32_e32 v250, 0x0, v241
	v_cvt_f32_u32_e32 v250, v250
	v_mul_f32_e32 v250, 0x39800000, v250
	v_cos_f32_e32 v218, v250
	v_sin_f32_e32 v219, v250
	s_nop 1
	v_xor_b32_e32 v219, 0x80000000, v219
	s_nop 0
	v_pk_mul_f32 v[122:123], v[218:219], v[218:219] op_sel:[1,1] op_sel_hi:[1,0]
	s_nop 0
	v_pk_fma_f32 v[220:221], v[218:219], v[218:219], v[122:123] op_sel_hi:[0,1,1] neg_lo:[0,0,1]
	s_nop 0
	v_pk_mul_f32 v[122:123], v[220:221], v[218:219] op_sel:[1,1] op_sel_hi:[1,0]
	s_nop 0
	v_pk_fma_f32 v[222:223], v[220:221], v[218:219], v[122:123] op_sel_hi:[0,1,1] neg_lo:[0,0,1]
	s_nop 0
	v_add_u32_e32 v250, 0x100, v241
	v_cvt_f32_u32_e32 v250, v250
	v_mul_f32_e32 v250, 0x39800000, v250
	v_cos_f32_e32 v224, v250
	v_sin_f32_e32 v225, v250
	s_nop 1
	v_xor_b32_e32 v225, 0x80000000, v225
	s_nop 0
	v_pk_mul_f32 v[122:123], v[224:225], v[224:225] op_sel:[1,1] op_sel_hi:[1,0]
	s_nop 0
	v_pk_fma_f32 v[226:227], v[224:225], v[224:225], v[122:123] op_sel_hi:[0,1,1] neg_lo:[0,0,1]
	s_nop 0
	v_pk_mul_f32 v[122:123], v[226:227], v[224:225] op_sel:[1,1] op_sel_hi:[1,0]
	s_nop 0
	v_pk_fma_f32 v[228:229], v[226:227], v[224:225], v[122:123] op_sel_hi:[0,1,1] neg_lo:[0,0,1]
	s_nop 0
	v_add_u32_e32 v250, 0x200, v241
	v_cvt_f32_u32_e32 v250, v250
	v_mul_f32_e32 v250, 0x39800000, v250
	v_cos_f32_e32 v230, v250
	v_sin_f32_e32 v231, v250
	s_nop 1
	v_xor_b32_e32 v231, 0x80000000, v231
	s_nop 0
	v_pk_mul_f32 v[122:123], v[230:231], v[230:231] op_sel:[1,1] op_sel_hi:[1,0]
	s_nop 0
	v_pk_fma_f32 v[232:233], v[230:231], v[230:231], v[122:123] op_sel_hi:[0,1,1] neg_lo:[0,0,1]
	s_nop 0
	v_pk_mul_f32 v[122:123], v[232:233], v[230:231] op_sel:[1,1] op_sel_hi:[1,0]
	s_nop 0
	v_pk_fma_f32 v[234:235], v[232:233], v[230:231], v[122:123] op_sel_hi:[0,1,1] neg_lo:[0,0,1]
	s_nop 0
	v_add_u32_e32 v250, 0x300, v241
	v_cvt_f32_u32_e32 v250, v250
	v_mul_f32_e32 v250, 0x39800000, v250
	v_cos_f32_e32 v236, v250
	v_sin_f32_e32 v237, v250
	s_nop 1
	v_xor_b32_e32 v237, 0x80000000, v237
	s_nop 0
	v_pk_mul_f32 v[122:123], v[236:237], v[236:237] op_sel:[1,1] op_sel_hi:[1,0]
	s_nop 0
	v_pk_fma_f32 v[238:239], v[236:237], v[236:237], v[122:123] op_sel_hi:[0,1,1] neg_lo:[0,0,1]
	s_nop 0
	v_pk_mul_f32 v[122:123], v[238:239], v[236:237] op_sel:[1,1] op_sel_hi:[1,0]
	s_nop 0
	v_pk_fma_f32 v[242:243], v[238:239], v[236:237], v[122:123] op_sel_hi:[0,1,1] neg_lo:[0,0,1]
	s_nop 0
	v_cvt_f32_u32_e32 v250, v241
	v_mul_f32_e32 v250, 0x3a800000, v250
	v_cos_f32_e32 v244, v250
	v_sin_f32_e32 v245, v250
	s_nop 1
	v_xor_b32_e32 v245, 0x80000000, v245
	s_nop 0
	v_pk_mul_f32 v[122:123], v[244:245], v[244:245] op_sel:[1,1] op_sel_hi:[1,0]
	s_nop 0
	v_pk_fma_f32 v[246:247], v[244:245], v[244:245], v[122:123] op_sel_hi:[0,1,1] neg_lo:[0,0,1]
	s_nop 0
	v_pk_mul_f32 v[122:123], v[246:247], v[244:245] op_sel:[1,1] op_sel_hi:[1,0]
	s_nop 0
	v_pk_fma_f32 v[248:249], v[246:247], v[244:245], v[122:123] op_sel_hi:[0,1,1] neg_lo:[0,0,1]
	s_nop 0

; DI float2 twid(float r) { return float2{__builtin_amdgcn_cosf(r), -__builtin_amdgcn_sinf(r)}; }
; DI void bfly_fwd(float2 a0, float2 a1, float2 a2, float2 a3, float r, float2& o0, float2& o1, float2& o2, float2& o3) {
;   float2 t0 = {a0.x + a2.x, a0.y + a2.y}, t1 = {a0.x - a2.x, a0.y - a2.y}, t2 = {a1.x + a3.x, a1.y + a3.y}, t3 = {a1.x - a3.x, a1.y - a3.y};
;   float2 b0 = {t0.x + t2.x, t0.y + t2.y}, b2 = {t0.x - t2.x, t0.y - t2.y}, b1 = {t1.x + t3.y, t1.y - t3.x}, b3 = {t1.x - t3.y, t1.y + t3.x};
;   float2 w1 = twid(r), w2 = cmul(w1, w1), w3 = cmul(w2, w1);
;   const int lq2 = lq1 - 2, Q1 = 1 << lq1, Q2 = 1 << lq2; const float invM1 = 1.f / (float)(4 << lq1), invM2 = 1.f / (float)(4 << lq2);
;   for (int gg = tid; gg < NBT * (N / 16); gg += NTHR) { const int g = gg & (N / 16 - 1); float2* z = z0 + (gg / (N / 16)) * N; const int jp = g & (Q2 - 1), base = ((g >> lq2) << (lq2 + 4)) + jp; float2 x[4][4];
; #pragma unroll
;     for (int q1 = 0; q1 < 4; ++q1)
; #pragma unroll
;       for (int q2 = 0; q2 < 4; ++q2) x[q1][q2] = z[base + q1 * Q1 + q2 * Q2];
; #pragma unroll
;     for (int q2 = 0; q2 < 4; ++q2) bfly_fwd(x[0][q2], x[1][q2], x[2][q2], x[3][q2], (float)(jp + q2 * Q2) * invM1, x[0][q2], x[1][q2], x[2][q2], x[3][q2]);
.LBB0_1601:
	s_or_b64 exec, exec, s[0:1]
	v_and_b32_e32 v2, 15, v75
	v_and_b32_e32 v66, 0xf800, v62
	v_lshlrev_b32_e32 v67, 3, v2
	v_cvt_f32_ubyte0_e32 v65, v2
	v_or_b32_e32 v64, 16, v2
	v_or_b32_e32 v63, 32, v2
	v_or_b32_e32 v62, 48, v2
	s_waitcnt lgkmcnt(0)
	s_barrier
	s_and_saveexec_b64 s[0:1], vcc
	s_cbranch_execz .LBB0_1604
	v_add3_u32 v68, 16, v66, v67
	s_mov_b64 s[80:81], 0
	v_mov_b32_e32 v69, v75
	v_and_b32_e32 v241, 0xf, v69
	v_add_u32_e32 v250, 0x0, v241
	v_cvt_f32_u32_e32 v250, v250
	v_mul_f32_e32 v250, 0x3b800000, v250
	v_cos_f32_e32 v218, v250
	v_sin_f32_e32 v219, v250
	s_nop 1
	v_xor_b32_e32 v219, 0x80000000, v219
	s_nop 0
	v_pk_mul_f32 v[128:129], v[218:219], v[218:219] op_sel:[1,1] op_sel_hi:[1,0]
	s_nop 0
	v_pk_fma_f32 v[220:221], v[218:219], v[218:219], v[128:129] op_sel_hi:[0,1,1] neg_lo:[0,0,1]
	s_nop 0
	v_pk_mul_f32 v[128:129], v[220:221], v[218:219] op_sel:[1,1] op_sel_hi:[1,0]
	s_nop 0
	v_pk_fma_f32 v[222:223], v[220:221], v[218:219], v[128:129] op_sel_hi:[0,1,1] neg_lo:[0,0,1]
	s_nop 0
	v_add_u32_e32 v250, 0x10, v241
	v_cvt_f32_u32_e32 v250, v250
	v_mul_f32_e32 v250, 0x3b800000, v250
	v_cos_f32_e32 v224, v250
	v_sin_f32_e32 v225, v250
	s_nop 1
	v_xor_b32_e32 v225, 0x80000000, v225
	s_nop 0
	v_pk_mul_f32 v[128:129], v[224:225], v[224:225] op_sel:[1,1] op_sel_hi:[1,0]
	s_nop 0
	v_pk_fma_f32 v[226:227], v[224:225], v[224:225], v[128:129] op_sel_hi:[0,1,1] neg_lo:[0,0,1]
	s_nop 0
	v_pk_mul_f32 v[128:129], v[226:227], v[224:225] op_sel:[1,1] op_sel_hi:[1,0]
	s_nop 0
	v_pk_fma_f32 v[228:229], v[226:227], v[224:225], v[128:129] op_sel_hi:[0,1,1] neg_lo:[0,0,1]
	s_nop 0
	v_add_u32_e32 v250, 0x20, v241
	v_cvt_f32_u32_e32 v250, v250
	v_mul_f32_e32 v250, 0x3b800000, v250
	v_cos_f32_e32 v230, v250
	v_sin_f32_e32 v231, v250
	s_nop 1
	v_xor_b32_e32 v231, 0x80000000, v231
	s_nop 0
	v_pk_mul_f32 v[128:129], v[230:231], v[230:231] op_sel:[1,1] op_sel_hi:[1,0]
	s_nop 0
	v_pk_fma_f32 v[232:233], v[230:231], v[230:231], v[128:129] op_sel_hi:[0,1,1] neg_lo:[0,0,1]
	s_nop 0
	v_pk_mul_f32 v[128:129], v[232:233], v[230:231] op_sel:[1,1] op_sel_hi:[1,0]
	s_nop 0
	v_pk_fma_f32 v[234:235], v[232:233], v[230:231], v[128:129] op_sel_hi:[0,1,1] neg_lo:[0,0,1]
	s_nop 0
	v_add_u32_e32 v250, 0x30, v241
	v_cvt_f32_u32_e32 v250, v250
	v_mul_f32_e32 v250, 0x3b800000, v250
	v_cos_f32_e32 v236, v250
	v_sin_f32_e32 v237, v250
	s_nop 1
	v_xor_b32_e32 v237, 0x80000000, v237
	s_nop 0
	v_pk_mul_f32 v[128:129], v[236:237], v[236:237] op_sel:[1,1] op_sel_hi:[1,0]
	s_nop 0
	v_pk_fma_f32 v[238:239], v[236:237], v[236:237], v[128:129] op_sel_hi:[0,1,1] neg_lo:[0,0,1]
	s_nop 0
	v_pk_mul_f32 v[128:129], v[238:239], v[236:237] op_sel:[1,1] op_sel_hi:[1,0]
	s_nop 0
	v_pk_fma_f32 v[242:243], v[238:239], v[236:237], v[128:129] op_sel_hi:[0,1,1] neg_lo:[0,0,1]
	s_nop 0
	v_cvt_f32_u32_e32 v250, v241
	v_mul_f32_e32 v250, 0x3c800000, v250
	v_cos_f32_e32 v244, v250
	v_sin_f32_e32 v245, v250
	s_nop 1
	v_xor_b32_e32 v245, 0x80000000, v245
	s_nop 0
	v_pk_mul_f32 v[128:129], v[244:245], v[244:245] op_sel:[1,1] op_sel_hi:[1,0]
	s_nop 0
	v_pk_fma_f32 v[246:247], v[244:245], v[244:245], v[128:129] op_sel_hi:[0,1,1] neg_lo:[0,0,1]
	s_nop 0
	v_pk_mul_f32 v[128:129], v[246:247], v[244:245] op_sel:[1,1] op_sel_hi:[1,0]
	s_nop 0
	v_pk_fma_f32 v[248:249], v[246:247], v[244:245], v[128:129] op_sel_hi:[0,1,1] neg_lo:[0,0,1]
	s_nop 0

; DI float2 twid(float r) { return float2{__builtin_amdgcn_cosf(r), -__builtin_amdgcn_sinf(r)}; }
; DI void bfly_inv(float2 s0, float2 s1, float2 s2, float2 s3, float r, float2& o0, float2& o1, float2& o2, float2& o3) {
;   float2 w1 = twid(r), w2 = cmul(w1, w1), w3 = cmul(w2, w1);
;   const int lq1 = lq2 + 2, Q1 = 1 << lq1, Q2 = 1 << lq2; const float invM1 = 1.f / (float)(4 << lq1), invM2 = 1.f / (float)(4 << lq2);
;   for (int gg = tid; gg < NBT * (N / 16); gg += NTHR) { const int g = gg & (N / 16 - 1); float2* z = z0 + (gg / (N / 16)) * N; const int jp = g & (Q2 - 1), base = ((g >> lq2) << (lq2 + 4)) + jp; float2 x[4][4];
; #pragma unroll
;     for (int q1 = 0; q1 < 4; ++q1)
; #pragma unroll
;       for (int q2 = 0; q2 < 4; ++q2) x[q1][q2] = z[base + q1 * Q1 + q2 * Q2];
; #pragma unroll
;     for (int q1 = 0; q1 < 4; ++q1) bfly_inv(x[q1][0], x[q1][1], x[q1][2], x[q1][3], (float)jp * invM2, x[q1][0], x[q1][1], x[q1][2], x[q1][3]);
; #pragma unroll
;     for (int q2 = 0; q2 < 4; ++q2) bfly_inv(x[0][q2], x[1][q2], x[2][q2], x[3][q2], (float)(jp + q2 * Q2) * invM1, x[0][q2], x[1][q2], x[2][q2], x[3][q2]);
.LBB0_1616:
	s_or_b64 exec, exec, s[0:1]
	s_waitcnt lgkmcnt(0)
	s_barrier
	s_and_saveexec_b64 s[0:1], vcc
	s_cbranch_execz .LBB0_1619
	v_add3_u32 v20, 16, v66, v67
	s_mov_b64 s[80:81], 0
	v_mov_b32_e32 v82, v75
	v_and_b32_e32 v241, 0xf, v82
	v_add_u32_e32 v250, 0x0, v241
	v_cvt_f32_u32_e32 v250, v250
	v_mul_f32_e32 v250, 0x3b800000, v250
	v_cos_f32_e32 v218, v250
	v_sin_f32_e32 v219, v250
	s_nop 1
	v_xor_b32_e32 v219, 0x80000000, v219
	s_nop 0
	v_pk_mul_f32 v[132:133], v[218:219], v[218:219] op_sel:[1,1] op_sel_hi:[1,0]
	s_nop 0
	v_pk_fma_f32 v[220:221], v[218:219], v[218:219], v[132:133] op_sel_hi:[0,1,1] neg_lo:[0,0,1]
	s_nop 0
	v_pk_mul_f32 v[132:133], v[220:221], v[218:219] op_sel:[1,1] op_sel_hi:[1,0]
	s_nop 0
	v_pk_fma_f32 v[222:223], v[220:221], v[218:219], v[132:133] op_sel_hi:[0,1,1] neg_lo:[0,0,1]
	s_nop 0
	v_xor_b32_e32 v219, 0x80000000, v219
	v_xor_b32_e32 v221, 0x80000000, v221
	v_xor_b32_e32 v223, 0x80000000, v223
	v_add_u32_e32 v250, 0x10, v241
	v_cvt_f32_u32_e32 v250, v250
	v_mul_f32_e32 v250, 0x3b800000, v250
	v_cos_f32_e32 v224, v250
	v_sin_f32_e32 v225, v250
	s_nop 1
	v_xor_b32_e32 v225, 0x80000000, v225
	s_nop 0
	v_pk_mul_f32 v[132:133], v[224:225], v[224:225] op_sel:[1,1] op_sel_hi:[1,0]
	s_nop 0
	v_pk_fma_f32 v[226:227], v[224:225], v[224:225], v[132:133] op_sel_hi:[0,1,1] neg_lo:[0,0,1]
	s_nop 0
	v_pk_mul_f32 v[132:133], v[226:227], v[224:225] op_sel:[1,1] op_sel_hi:[1,0]
	s_nop 0
	v_pk_fma_f32 v[228:229], v[226:227], v[224:225], v[132:133] op_sel_hi:[0,1,1] neg_lo:[0,0,1]
	s_nop 0
	v_xor_b32_e32 v225, 0x80000000, v225
	v_xor_b32_e32 v227, 0x80000000, v227
	v_xor_b32_e32 v229, 0x80000000, v229
	v_add_u32_e32 v250, 0x20, v241
	v_cvt_f32_u32_e32 v250, v250
	v_mul_f32_e32 v250, 0x3b800000, v250
	v_cos_f32_e32 v230, v250
	v_sin_f32_e32 v231, v250
	s_nop 1
	v_xor_b32_e32 v231, 0x80000000, v231
	s_nop 0
	v_pk_mul_f32 v[132:133], v[230:231], v[230:231] op_sel:[1,1] op_sel_hi:[1,0]
	s_nop 0
	v_pk_fma_f32 v[232:233], v[230:231], v[230:231], v[132:133] op_sel_hi:[0,1,1] neg_lo:[0,0,1]
	s_nop 0
	v_pk_mul_f32 v[132:133], v[232:233], v[230:231] op_sel:[1,1] op_sel_hi:[1,0]
	s_nop 0
	v_pk_fma_f32 v[234:235], v[232:233], v[230:231], v[132:133] op_sel_hi:[0,1,1] neg_lo:[0,0,1]
	s_nop 0
	v_xor_b32_e32 v231, 0x80000000, v231
	v_xor_b32_e32 v233, 0x80000000, v233
	v_xor_b32_e32 v235, 0x80000000, v235
	v_add_u32_e32 v250, 0x30, v241
	v_cvt_f32_u32_e32 v250, v250
	v_mul_f32_e32 v250, 0x3b800000, v250
	v_cos_f32_e32 v236, v250
	v_sin_f32_e32 v237, v250
	s_nop 1
	v_xor_b32_e32 v237, 0x80000000, v237
	s_nop 0
	v_pk_mul_f32 v[132:133], v[236:237], v[236:237] op_sel:[1,1] op_sel_hi:[1,0]
	s_nop 0
	v_pk_fma_f32 v[238:239], v[236:237], v[236:237], v[132:133] op_sel_hi:[0,1,1] neg_lo:[0,0,1]
	s_nop 0
	v_pk_mul_f32 v[132:133], v[238:239], v[236:237] op_sel:[1,1] op_sel_hi:[1,0]
	s_nop 0
	v_pk_fma_f32 v[242:243], v[238:239], v[236:237], v[132:133] op_sel_hi:[0,1,1] neg_lo:[0,0,1]
	s_nop 0
	v_xor_b32_e32 v237, 0x80000000, v237
	v_xor_b32_e32 v239, 0x80000000, v239
	v_xor_b32_e32 v243, 0x80000000, v243
	v_cvt_f32_u32_e32 v250, v241
	v_mul_f32_e32 v250, 0x3c800000, v250
	v_cos_f32_e32 v244, v250
	v_sin_f32_e32 v245, v250
	s_nop 1
	v_xor_b32_e32 v245, 0x80000000, v245
	s_nop 0
	v_pk_mul_f32 v[132:133], v[244:245], v[244:245] op_sel:[1,1] op_sel_hi:[1,0]
	s_nop 0
	v_pk_fma_f32 v[246:247], v[244:245], v[244:245], v[132:133] op_sel_hi:[0,1,1] neg_lo:[0,0,1]
	s_nop 0
	v_pk_mul_f32 v[132:133], v[246:247], v[244:245] op_sel:[1,1] op_sel_hi:[1,0]
	s_nop 0
	v_pk_fma_f32 v[248:249], v[246:247], v[244:245], v[132:133] op_sel_hi:[0,1,1] neg_lo:[0,0,1]
	s_nop 0
	v_xor_b32_e32 v245, 0x80000000, v245
	v_xor_b32_e32 v247, 0x80000000, v247
	v_xor_b32_e32 v249, 0x80000000, v249

; DI float2 twid(float r) { return float2{__builtin_amdgcn_cosf(r), -__builtin_amdgcn_sinf(r)}; }
; DI void bfly_inv(float2 s0, float2 s1, float2 s2, float2 s3, float r, float2& o0, float2& o1, float2& o2, float2& o3) {
;   float2 w1 = twid(r), w2 = cmul(w1, w1), w3 = cmul(w2, w1);
;   const int lq1 = lq2 + 2, Q1 = 1 << lq1, Q2 = 1 << lq2; const float invM1 = 1.f / (float)(4 << lq1), invM2 = 1.f / (float)(4 << lq2);
;   for (int gg = tid; gg < NBT * (N / 16); gg += NTHR) { const int g = gg & (N / 16 - 1); float2* z = z0 + (gg / (N / 16)) * N; const int jp = g & (Q2 - 1), base = ((g >> lq2) << (lq2 + 4)) + jp; float2 x[4][4];
; #pragma unroll
;     for (int q1 = 0; q1 < 4; ++q1)
; #pragma unroll
;       for (int q2 = 0; q2 < 4; ++q2) x[q1][q2] = z[base + q1 * Q1 + q2 * Q2];
; #pragma unroll
;     for (int q1 = 0; q1 < 4; ++q1) bfly_inv(x[q1][0], x[q1][1], x[q1][2], x[q1][3], (float)jp * invM2, x[q1][0], x[q1][1], x[q1][2], x[q1][3]);
; #pragma unroll
;     for (int q2 = 0; q2 < 4; ++q2) bfly_inv(x[0][q2], x[1][q2], x[2][q2], x[3][q2], (float)(jp + q2 * Q2) * invM1, x[0][q2], x[1][q2], x[2][q2], x[3][q2]);
.LBB0_1619:
	s_or_b64 exec, exec, s[0:1]
	s_waitcnt lgkmcnt(0)
	s_barrier
	s_and_saveexec_b64 s[12:13], vcc
	s_cbranch_execz .LBB0_1622
	v_cvt_f32_u32_e32 v9, v76
	v_mul_f32_e32 v6, 0x39800000, v9
	v_sin_f32_e32 v33, v6
	v_cos_f32_e32 v35, v6
	v_mul_f32_e32 v6, v33, v33
	v_fma_f32 v36, v35, v35, -v6
	v_mul_f32_e32 v0, v33, v36
	v_add3_u32 v20, 16, v79, v80
	s_mov_b64 s[0:1], 0
	v_and_b32_e32 v241, 0xff, v75
	v_add_u32_e32 v250, 0x0, v241
	v_cvt_f32_u32_e32 v250, v250
	v_mul_f32_e32 v250, 0x39800000, v250
	v_cos_f32_e32 v218, v250
	v_sin_f32_e32 v219, v250
	s_nop 1
	v_xor_b32_e32 v219, 0x80000000, v219
	s_nop 0
	v_pk_mul_f32 v[124:125], v[218:219], v[218:219] op_sel:[1,1] op_sel_hi:[1,0]
	s_nop 0
	v_pk_fma_f32 v[220:221], v[218:219], v[218:219], v[124:125] op_sel_hi:[0,1,1] neg_lo:[0,0,1]
	s_nop 0
	v_pk_mul_f32 v[124:125], v[220:221], v[218:219] op_sel:[1,1] op_sel_hi:[1,0]
	s_nop 0
	v_pk_fma_f32 v[222:223], v[220:221], v[218:219], v[124:125] op_sel_hi:[0,1,1] neg_lo:[0,0,1]
	s_nop 0
	v_xor_b32_e32 v219, 0x80000000, v219
	v_xor_b32_e32 v221, 0x80000000, v221
	v_xor_b32_e32 v223, 0x80000000, v223
	v_add_u32_e32 v250, 0x100, v241
	v_cvt_f32_u32_e32 v250, v250
	v_mul_f32_e32 v250, 0x39800000, v250
	v_cos_f32_e32 v224, v250
	v_sin_f32_e32 v225, v250
	s_nop 1
	v_xor_b32_e32 v225, 0x80000000, v225
	s_nop 0
	v_pk_mul_f32 v[124:125], v[224:225], v[224:225] op_sel:[1,1] op_sel_hi:[1,0]
	s_nop 0
	v_pk_fma_f32 v[226:227], v[224:225], v[224:225], v[124:125] op_sel_hi:[0,1,1] neg_lo:[0,0,1]
	s_nop 0
	v_pk_mul_f32 v[124:125], v[226:227], v[224:225] op_sel:[1,1] op_sel_hi:[1,0]
	s_nop 0
	v_pk_fma_f32 v[228:229], v[226:227], v[224:225], v[124:125] op_sel_hi:[0,1,1] neg_lo:[0,0,1]
	s_nop 0
	v_xor_b32_e32 v225, 0x80000000, v225
	v_xor_b32_e32 v227, 0x80000000, v227
	v_xor_b32_e32 v229, 0x80000000, v229
	v_add_u32_e32 v250, 0x200, v241
	v_cvt_f32_u32_e32 v250, v250
	v_mul_f32_e32 v250, 0x39800000, v250
	v_cos_f32_e32 v230, v250
	v_sin_f32_e32 v231, v250
	s_nop 1
	v_xor_b32_e32 v231, 0x80000000, v231
	s_nop 0
	v_pk_mul_f32 v[124:125], v[230:231], v[230:231] op_sel:[1,1] op_sel_hi:[1,0]
	s_nop 0
	v_pk_fma_f32 v[232:233], v[230:231], v[230:231], v[124:125] op_sel_hi:[0,1,1] neg_lo:[0,0,1]
	s_nop 0
	v_pk_mul_f32 v[124:125], v[232:233], v[230:231] op_sel:[1,1] op_sel_hi:[1,0]
	s_nop 0
	v_pk_fma_f32 v[234:235], v[232:233], v[230:231], v[124:125] op_sel_hi:[0,1,1] neg_lo:[0,0,1]
	s_nop 0
	v_xor_b32_e32 v231, 0x80000000, v231
	v_xor_b32_e32 v233, 0x80000000, v233
	v_xor_b32_e32 v235, 0x80000000, v235
	v_add_u32_e32 v250, 0x300, v241
	v_cvt_f32_u32_e32 v250, v250
	v_mul_f32_e32 v250, 0x39800000, v250
	v_cos_f32_e32 v236, v250
	v_sin_f32_e32 v237, v250
	s_nop 1
	v_xor_b32_e32 v237, 0x80000000, v237
	s_nop 0
	v_pk_mul_f32 v[124:125], v[236:237], v[236:237] op_sel:[1,1] op_sel_hi:[1,0]
	s_nop 0
	v_pk_fma_f32 v[238:239], v[236:237], v[236:237], v[124:125] op_sel_hi:[0,1,1] neg_lo:[0,0,1]
	s_nop 0
	v_pk_mul_f32 v[124:125], v[238:239], v[236:237] op_sel:[1,1] op_sel_hi:[1,0]
	s_nop 0
	v_pk_fma_f32 v[242:243], v[238:239], v[236:237], v[124:125] op_sel_hi:[0,1,1] neg_lo:[0,0,1]
	s_nop 0
	v_xor_b32_e32 v237, 0x80000000, v237
	v_xor_b32_e32 v239, 0x80000000, v239
	v_xor_b32_e32 v243, 0x80000000, v243
	v_cvt_f32_u32_e32 v250, v241
	v_mul_f32_e32 v250, 0x3a800000, v250
	v_cos_f32_e32 v244, v250
	v_sin_f32_e32 v245, v250
	s_nop 1
	v_xor_b32_e32 v245, 0x80000000, v245
	s_nop 0
	v_pk_mul_f32 v[124:125], v[244:245], v[244:245] op_sel:[1,1] op_sel_hi:[1,0]
	s_nop 0
	v_pk_fma_f32 v[246:247], v[244:245], v[244:245], v[124:125] op_sel_hi:[0,1,1] neg_lo:[0,0,1]
	s_nop 0
	v_pk_mul_f32 v[124:125], v[246:247], v[244:245] op_sel:[1,1] op_sel_hi:[1,0]
	s_nop 0
	v_pk_fma_f32 v[248:249], v[246:247], v[244:245], v[124:125] op_sel_hi:[0,1,1] neg_lo:[0,0,1]
	s_nop 0
	v_xor_b32_e32 v245, 0x80000000, v245
	v_xor_b32_e32 v247, 0x80000000, v247
	v_xor_b32_e32 v249, 0x80000000, v249

; DI float2 twid(float r) { return float2{__builtin_amdgcn_cosf(r), -__builtin_amdgcn_sinf(r)}; }
; DI void bfly_fwd(float2 a0, float2 a1, float2 a2, float2 a3, float r, float2& o0, float2& o1, float2& o2, float2& o3) {
;   float2 t0 = {a0.x + a2.x, a0.y + a2.y}, t1 = {a0.x - a2.x, a0.y - a2.y}, t2 = {a1.x + a3.x, a1.y + a3.y}, t3 = {a1.x - a3.x, a1.y - a3.y};
;   float2 b0 = {t0.x + t2.x, t0.y + t2.y}, b2 = {t0.x - t2.x, t0.y - t2.y}, b1 = {t1.x + t3.y, t1.y - t3.x}, b3 = {t1.x - t3.y, t1.y + t3.x};
;   float2 w1 = twid(r), w2 = cmul(w1, w1), w3 = cmul(w2, w1);
;   const int lq2 = lq1 - 2, Q1 = 1 << lq1, Q2 = 1 << lq2; const float invM1 = 1.f / (float)(4 << lq1), invM2 = 1.f / (float)(4 << lq2);
;   for (int gg = tid; gg < NBT * (N / 16); gg += NTHR) { const int g = gg & (N / 16 - 1); float2* z = z0 + (gg / (N / 16)) * N; const int jp = g & (Q2 - 1), base = ((g >> lq2) << (lq2 + 4)) + jp; float2 x[4][4];
; #pragma unroll
;     for (int q1 = 0; q1 < 4; ++q1)
; #pragma unroll
;       for (int q2 = 0; q2 < 4; ++q2) x[q1][q2] = z[base + q1 * Q1 + q2 * Q2];
; #pragma unroll
;     for (int q2 = 0; q2 < 4; ++q2) bfly_fwd(x[0][q2], x[1][q2], x[2][q2], x[3][q2], (float)(jp + q2 * Q2) * invM1, x[0][q2], x[1][q2], x[2][q2], x[3][q2]);
.LBB0_1630:
	s_or_b64 exec, exec, s[0:1]
	s_movk_i32 s0, 0x400
	v_cmp_gt_i32_e32 vcc, s0, v76
	s_movk_i32 s0, 0x100
	v_or_b32_sdwa v80, v76, s0 dst_sel:DWORD dst_unused:UNUSED_PAD src0_sel:BYTE_0 src1_sel:DWORD
	s_movk_i32 s0, 0x200
	v_cvt_f32_ubyte0_e32 v4, v76
	v_or_b32_sdwa v79, v76, s0 dst_sel:DWORD dst_unused:UNUSED_PAD src0_sel:BYTE_0 src1_sel:DWORD
	s_movk_i32 s0, 0x300
	v_mul_f32_e32 v81, 0x39800000, v4
	v_or_b32_sdwa v78, v76, s0 dst_sel:DWORD dst_unused:UNUSED_PAD src0_sel:BYTE_0 src1_sel:DWORD
	v_mul_f32_e32 v82, 0x3a800000, v4
	v_lshlrev_b32_e32 v77, 4, v76
	s_waitcnt lgkmcnt(0)
	s_barrier
	s_and_saveexec_b64 s[0:1], vcc
	s_cbranch_execz .LBB0_1633
	v_lshlrev_b32_e32 v64, 4, v76
	s_mov_b64 s[14:15], 0
	v_mov_b32_e32 v65, v76
	v_and_b32_e32 v241, 0xff, v65
	v_add_u32_e32 v250, 0x0, v241
	v_cvt_f32_u32_e32 v250, v250
	v_mul_f32_e32 v250, 0x39800000, v250
	v_cos_f32_e32 v218, v250
	v_sin_f32_e32 v219, v250
	s_nop 1
	v_xor_b32_e32 v219, 0x80000000, v219
	s_nop 0
	v_pk_mul_f32 v[126:127], v[218:219], v[218:219] op_sel:[1,1] op_sel_hi:[1,0]
	s_nop 0
	v_pk_fma_f32 v[220:221], v[218:219], v[218:219], v[126:127] op_sel_hi:[0,1,1] neg_lo:[0,0,1]
	s_nop 0
	v_pk_mul_f32 v[126:127], v[220:221], v[218:219] op_sel:[1,1] op_sel_hi:[1,0]
	s_nop 0
	v_pk_fma_f32 v[222:223], v[220:221], v[218:219], v[126:127] op_sel_hi:[0,1,1] neg_lo:[0,0,1]
	s_nop 0
	v_add_u32_e32 v250, 0x100, v241
	v_cvt_f32_u32_e32 v250, v250
	v_mul_f32_e32 v250, 0x39800000, v250
	v_cos_f32_e32 v224, v250
	v_sin_f32_e32 v225, v250
	s_nop 1
	v_xor_b32_e32 v225, 0x80000000, v225
	s_nop 0
	v_pk_mul_f32 v[126:127], v[224:225], v[224:225] op_sel:[1,1] op_sel_hi:[1,0]
	s_nop 0
	v_pk_fma_f32 v[226:227], v[224:225], v[224:225], v[126:127] op_sel_hi:[0,1,1] neg_lo:[0,0,1]
	s_nop 0
	v_pk_mul_f32 v[126:127], v[226:227], v[224:225] op_sel:[1,1] op_sel_hi:[1,0]
	s_nop 0
	v_pk_fma_f32 v[228:229], v[226:227], v[224:225], v[126:127] op_sel_hi:[0,1,1] neg_lo:[0,0,1]
	s_nop 0
	v_add_u32_e32 v250, 0x200, v241
	v_cvt_f32_u32_e32 v250, v250
	v_mul_f32_e32 v250, 0x39800000, v250
	v_cos_f32_e32 v230, v250
	v_sin_f32_e32 v231, v250
	s_nop 1
	v_xor_b32_e32 v231, 0x80000000, v231
	s_nop 0
	v_pk_mul_f32 v[126:127], v[230:231], v[230:231] op_sel:[1,1] op_sel_hi:[1,0]
	s_nop 0
	v_pk_fma_f32 v[232:233], v[230:231], v[230:231], v[126:127] op_sel_hi:[0,1,1] neg_lo:[0,0,1]
	s_nop 0
	v_pk_mul_f32 v[126:127], v[232:233], v[230:231] op_sel:[1,1] op_sel_hi:[1,0]
	s_nop 0
	v_pk_fma_f32 v[234:235], v[232:233], v[230:231], v[126:127] op_sel_hi:[0,1,1] neg_lo:[0,0,1]
	s_nop 0
	v_add_u32_e32 v250, 0x300, v241
	v_cvt_f32_u32_e32 v250, v250
	v_mul_f32_e32 v250, 0x39800000, v250
	v_cos_f32_e32 v236, v250
	v_sin_f32_e32 v237, v250
	s_nop 1
	v_xor_b32_e32 v237, 0x80000000, v237
	s_nop 0
	v_pk_mul_f32 v[126:127], v[236:237], v[236:237] op_sel:[1,1] op_sel_hi:[1,0]
	s_nop 0
	v_pk_fma_f32 v[238:239], v[236:237], v[236:237], v[126:127] op_sel_hi:[0,1,1] neg_lo:[0,0,1]
	s_nop 0
	v_pk_mul_f32 v[126:127], v[238:239], v[236:237] op_sel:[1,1] op_sel_hi:[1,0]
	s_nop 0
	v_pk_fma_f32 v[242:243], v[238:239], v[236:237], v[126:127] op_sel_hi:[0,1,1] neg_lo:[0,0,1]
	s_nop 0
	v_cvt_f32_u32_e32 v250, v241
	v_mul_f32_e32 v250, 0x3a800000, v250
	v_cos_f32_e32 v244, v250
	v_sin_f32_e32 v245, v250
	s_nop 1
	v_xor_b32_e32 v245, 0x80000000, v245
	s_nop 0
	v_pk_mul_f32 v[126:127], v[244:245], v[244:245] op_sel:[1,1] op_sel_hi:[1,0]
	s_nop 0
	v_pk_fma_f32 v[246:247], v[244:245], v[244:245], v[126:127] op_sel_hi:[0,1,1] neg_lo:[0,0,1]
	s_nop 0
	v_pk_mul_f32 v[126:127], v[246:247], v[244:245] op_sel:[1,1] op_sel_hi:[1,0]
	s_nop 0
	v_pk_fma_f32 v[248:249], v[246:247], v[244:245], v[126:127] op_sel_hi:[0,1,1] neg_lo:[0,0,1]
	s_nop 0

; DI float2 twid(float r) { return float2{__builtin_amdgcn_cosf(r), -__builtin_amdgcn_sinf(r)}; }
; DI void bfly_fwd(float2 a0, float2 a1, float2 a2, float2 a3, float r, float2& o0, float2& o1, float2& o2, float2& o3) {
;   float2 t0 = {a0.x + a2.x, a0.y + a2.y}, t1 = {a0.x - a2.x, a0.y - a2.y}, t2 = {a1.x + a3.x, a1.y + a3.y}, t3 = {a1.x - a3.x, a1.y - a3.y};
;   float2 b0 = {t0.x + t2.x, t0.y + t2.y}, b2 = {t0.x - t2.x, t0.y - t2.y}, b1 = {t1.x + t3.y, t1.y - t3.x}, b3 = {t1.x - t3.y, t1.y + t3.x};
;   float2 w1 = twid(r), w2 = cmul(w1, w1), w3 = cmul(w2, w1);
;   const int lq2 = lq1 - 2, Q1 = 1 << lq1, Q2 = 1 << lq2; const float invM1 = 1.f / (float)(4 << lq1), invM2 = 1.f / (float)(4 << lq2);
;   for (int gg = tid; gg < NBT * (N / 16); gg += NTHR) { const int g = gg & (N / 16 - 1); float2* z = z0 + (gg / (N / 16)) * N; const int jp = g & (Q2 - 1), base = ((g >> lq2) << (lq2 + 4)) + jp; float2 x[4][4];
; #pragma unroll
;     for (int q1 = 0; q1 < 4; ++q1)
; #pragma unroll
;       for (int q2 = 0; q2 < 4; ++q2) x[q1][q2] = z[base + q1 * Q1 + q2 * Q2];
; #pragma unroll
;     for (int q2 = 0; q2 < 4; ++q2) bfly_fwd(x[0][q2], x[1][q2], x[2][q2], x[3][q2], (float)(jp + q2 * Q2) * invM1, x[0][q2], x[1][q2], x[2][q2], x[3][q2]);
.LBB0_1633:
	s_or_b64 exec, exec, s[0:1]
	v_and_b32_e32 v83, 15, v76
	v_cvt_f32_ubyte0_e32 v67, v83
	v_or_b32_e32 v66, 16, v83
	v_or_b32_e32 v65, 32, v83
	v_or_b32_e32 v64, 48, v83
	s_waitcnt lgkmcnt(0)
	s_barrier
	s_and_saveexec_b64 s[0:1], vcc
	s_cbranch_execz .LBB0_1636
	v_lshlrev_b32_e32 v68, 4, v76
	s_mov_b64 s[14:15], 0
	v_mov_b32_e32 v69, v76
	v_and_b32_e32 v241, 0xf, v69
	v_add_u32_e32 v250, 0x0, v241
	v_cvt_f32_u32_e32 v250, v250
	v_mul_f32_e32 v250, 0x3b800000, v250
	v_cos_f32_e32 v218, v250
	v_sin_f32_e32 v219, v250
	s_nop 1
	v_xor_b32_e32 v219, 0x80000000, v219
	s_nop 0
	v_pk_mul_f32 v[130:131], v[218:219], v[218:219] op_sel:[1,1] op_sel_hi:[1,0]
	s_nop 0
	v_pk_fma_f32 v[220:221], v[218:219], v[218:219], v[130:131] op_sel_hi:[0,1,1] neg_lo:[0,0,1]
	s_nop 0
	v_pk_mul_f32 v[130:131], v[220:221], v[218:219] op_sel:[1,1] op_sel_hi:[1,0]
	s_nop 0
	v_pk_fma_f32 v[222:223], v[220:221], v[218:219], v[130:131] op_sel_hi:[0,1,1] neg_lo:[0,0,1]
	s_nop 0
	v_add_u32_e32 v250, 0x10, v241
	v_cvt_f32_u32_e32 v250, v250
	v_mul_f32_e32 v250, 0x3b800000, v250
	v_cos_f32_e32 v224, v250
	v_sin_f32_e32 v225, v250
	s_nop 1
	v_xor_b32_e32 v225, 0x80000000, v225
	s_nop 0
	v_pk_mul_f32 v[130:131], v[224:225], v[224:225] op_sel:[1,1] op_sel_hi:[1,0]
	s_nop 0
	v_pk_fma_f32 v[226:227], v[224:225], v[224:225], v[130:131] op_sel_hi:[0,1,1] neg_lo:[0,0,1]
	s_nop 0
	v_pk_mul_f32 v[130:131], v[226:227], v[224:225] op_sel:[1,1] op_sel_hi:[1,0]
	s_nop 0
	v_pk_fma_f32 v[228:229], v[226:227], v[224:225], v[130:131] op_sel_hi:[0,1,1] neg_lo:[0,0,1]
	s_nop 0
	v_add_u32_e32 v250, 0x20, v241
	v_cvt_f32_u32_e32 v250, v250
	v_mul_f32_e32 v250, 0x3b800000, v250
	v_cos_f32_e32 v230, v250
	v_sin_f32_e32 v231, v250
	s_nop 1
	v_xor_b32_e32 v231, 0x80000000, v231
	s_nop 0
	v_pk_mul_f32 v[130:131], v[230:231], v[230:231] op_sel:[1,1] op_sel_hi:[1,0]
	s_nop 0
	v_pk_fma_f32 v[232:233], v[230:231], v[230:231], v[130:131] op_sel_hi:[0,1,1] neg_lo:[0,0,1]
	s_nop 0
	v_pk_mul_f32 v[130:131], v[232:233], v[230:231] op_sel:[1,1] op_sel_hi:[1,0]
	s_nop 0
	v_pk_fma_f32 v[234:235], v[232:233], v[230:231], v[130:131] op_sel_hi:[0,1,1] neg_lo:[0,0,1]
	s_nop 0
	v_add_u32_e32 v250, 0x30, v241
	v_cvt_f32_u32_e32 v250, v250
	v_mul_f32_e32 v250, 0x3b800000, v250
	v_cos_f32_e32 v236, v250
	v_sin_f32_e32 v237, v250
	s_nop 1
	v_xor_b32_e32 v237, 0x80000000, v237
	s_nop 0
	v_pk_mul_f32 v[130:131], v[236:237], v[236:237] op_sel:[1,1] op_sel_hi:[1,0]
	s_nop 0
	v_pk_fma_f32 v[238:239], v[236:237], v[236:237], v[130:131] op_sel_hi:[0,1,1] neg_lo:[0,0,1]
	s_nop 0
	v_pk_mul_f32 v[130:131], v[238:239], v[236:237] op_sel:[1,1] op_sel_hi:[1,0]
	s_nop 0
	v_pk_fma_f32 v[242:243], v[238:239], v[236:237], v[130:131] op_sel_hi:[0,1,1] neg_lo:[0,0,1]
	s_nop 0
	v_cvt_f32_u32_e32 v250, v241
	v_mul_f32_e32 v250, 0x3c800000, v250
	v_cos_f32_e32 v244, v250
	v_sin_f32_e32 v245, v250
	s_nop 1
	v_xor_b32_e32 v245, 0x80000000, v245
	s_nop 0
	v_pk_mul_f32 v[130:131], v[244:245], v[244:245] op_sel:[1,1] op_sel_hi:[1,0]
	s_nop 0
	v_pk_fma_f32 v[246:247], v[244:245], v[244:245], v[130:131] op_sel_hi:[0,1,1] neg_lo:[0,0,1]
	s_nop 0
	v_pk_mul_f32 v[130:131], v[246:247], v[244:245] op_sel:[1,1] op_sel_hi:[1,0]
	s_nop 0
	v_pk_fma_f32 v[248:249], v[246:247], v[244:245], v[130:131] op_sel_hi:[0,1,1] neg_lo:[0,0,1]
	s_nop 0

; DI float2 twid(float r) { return float2{__builtin_amdgcn_cosf(r), -__builtin_amdgcn_sinf(r)}; }
; DI void bfly_inv(float2 s0, float2 s1, float2 s2, float2 s3, float r, float2& o0, float2& o1, float2& o2, float2& o3) {
;   float2 w1 = twid(r), w2 = cmul(w1, w1), w3 = cmul(w2, w1);
;   float2 c0 = s0, c1 = cmulc(s1, w1), c2 = cmulc(s2, w2), c3 = cmulc(s3, w3);
;   const int lq1 = lq2 + 2, Q1 = 1 << lq1, Q2 = 1 << lq2; const float invM1 = 1.f / (float)(4 << lq1), invM2 = 1.f / (float)(4 << lq2);
;   for (int gg = tid; gg < NBT * (N / 16); gg += NTHR) { const int g = gg & (N / 16 - 1); float2* z = z0 + (gg / (N / 16)) * N; const int jp = g & (Q2 - 1), base = ((g >> lq2) << (lq2 + 4)) + jp; float2 x[4][4];
; #pragma unroll
;     for (int q1 = 0; q1 < 4; ++q1)
; #pragma unroll
;       for (int q2 = 0; q2 < 4; ++q2) x[q1][q2] = z[base + q1 * Q1 + q2 * Q2];
; #pragma unroll
;     for (int q1 = 0; q1 < 4; ++q1) bfly_inv(x[q1][0], x[q1][1], x[q1][2], x[q1][3], (float)jp * invM2, x[q1][0], x[q1][1], x[q1][2], x[q1][3]);
; #pragma unroll
;     for (int q2 = 0; q2 < 4; ++q2) bfly_inv(x[0][q2], x[1][q2], x[2][q2], x[3][q2], (float)(jp + q2 * Q2) * invM1, x[0][q2], x[1][q2], x[2][q2], x[3][q2]);
.LBB0_1648:
	s_or_b64 exec, exec, s[0:1]
	s_waitcnt lgkmcnt(0)
	s_barrier
	s_and_saveexec_b64 s[14:15], vcc
	s_cbranch_execz .LBB0_1651
	s_mov_b64 s[0:1], 0
	v_mov_b32_e32 v84, v76
	v_lshlrev_b32_e32 v62, 4, v76
	v_and_b32_e32 v241, 0xf, v84
	v_add_u32_e32 v250, 0x0, v241
	v_cvt_f32_u32_e32 v250, v250
	v_mul_f32_e32 v250, 0x3b800000, v250
	v_cos_f32_e32 v218, v250
	v_sin_f32_e32 v219, v250
	s_nop 1
	v_xor_b32_e32 v219, 0x80000000, v219
	s_nop 0
	v_pk_mul_f32 v[134:135], v[218:219], v[218:219] op_sel:[1,1] op_sel_hi:[1,0]
	s_nop 0
	v_pk_fma_f32 v[220:221], v[218:219], v[218:219], v[134:135] op_sel_hi:[0,1,1] neg_lo:[0,0,1]
	s_nop 0
	v_pk_mul_f32 v[134:135], v[220:221], v[218:219] op_sel:[1,1] op_sel_hi:[1,0]
	s_nop 0
	v_pk_fma_f32 v[222:223], v[220:221], v[218:219], v[134:135] op_sel_hi:[0,1,1] neg_lo:[0,0,1]
	s_nop 0
	v_xor_b32_e32 v219, 0x80000000, v219
	v_xor_b32_e32 v221, 0x80000000, v221
	v_xor_b32_e32 v223, 0x80000000, v223
	v_add_u32_e32 v250, 0x10, v241
	v_cvt_f32_u32_e32 v250, v250
	v_mul_f32_e32 v250, 0x3b800000, v250
	v_cos_f32_e32 v224, v250
	v_sin_f32_e32 v225, v250
	s_nop 1
	v_xor_b32_e32 v225, 0x80000000, v225
	s_nop 0
	v_pk_mul_f32 v[134:135], v[224:225], v[224:225] op_sel:[1,1] op_sel_hi:[1,0]
	s_nop 0
	v_pk_fma_f32 v[226:227], v[224:225], v[224:225], v[134:135] op_sel_hi:[0,1,1] neg_lo:[0,0,1]
	s_nop 0
	v_pk_mul_f32 v[134:135], v[226:227], v[224:225] op_sel:[1,1] op_sel_hi:[1,0]
	s_nop 0
	v_pk_fma_f32 v[228:229], v[226:227], v[224:225], v[134:135] op_sel_hi:[0,1,1] neg_lo:[0,0,1]
	s_nop 0
	v_xor_b32_e32 v225, 0x80000000, v225
	v_xor_b32_e32 v227, 0x80000000, v227
	v_xor_b32_e32 v229, 0x80000000, v229
	v_add_u32_e32 v250, 0x20, v241
	v_cvt_f32_u32_e32 v250, v250
	v_mul_f32_e32 v250, 0x3b800000, v250
	v_cos_f32_e32 v230, v250
	v_sin_f32_e32 v231, v250
	s_nop 1
	v_xor_b32_e32 v231, 0x80000000, v231
	s_nop 0
	v_pk_mul_f32 v[134:135], v[230:231], v[230:231] op_sel:[1,1] op_sel_hi:[1,0]
	s_nop 0
	v_pk_fma_f32 v[232:233], v[230:231], v[230:231], v[134:135] op_sel_hi:[0,1,1] neg_lo:[0,0,1]
	s_nop 0
	v_pk_mul_f32 v[134:135], v[232:233], v[230:231] op_sel:[1,1] op_sel_hi:[1,0]
	s_nop 0
	v_pk_fma_f32 v[234:235], v[232:233], v[230:231], v[134:135] op_sel_hi:[0,1,1] neg_lo:[0,0,1]
	s_nop 0
	v_xor_b32_e32 v231, 0x80000000, v231
	v_xor_b32_e32 v233, 0x80000000, v233
	v_xor_b32_e32 v235, 0x80000000, v235
	v_add_u32_e32 v250, 0x30, v241
	v_cvt_f32_u32_e32 v250, v250
	v_mul_f32_e32 v250, 0x3b800000, v250
	v_cos_f32_e32 v236, v250
	v_sin_f32_e32 v237, v250
	s_nop 1
	v_xor_b32_e32 v237, 0x80000000, v237
	s_nop 0
	v_pk_mul_f32 v[134:135], v[236:237], v[236:237] op_sel:[1,1] op_sel_hi:[1,0]
	s_nop 0
	v_pk_fma_f32 v[238:239], v[236:237], v[236:237], v[134:135] op_sel_hi:[0,1,1] neg_lo:[0,0,1]
	s_nop 0
	v_pk_mul_f32 v[134:135], v[238:239], v[236:237] op_sel:[1,1] op_sel_hi:[1,0]
	s_nop 0
	v_pk_fma_f32 v[242:243], v[238:239], v[236:237], v[134:135] op_sel_hi:[0,1,1] neg_lo:[0,0,1]
	s_nop 0
	v_xor_b32_e32 v237, 0x80000000, v237
	v_xor_b32_e32 v239, 0x80000000, v239
	v_xor_b32_e32 v243, 0x80000000, v243
	v_cvt_f32_u32_e32 v250, v241
	v_mul_f32_e32 v250, 0x3c800000, v250
	v_cos_f32_e32 v244, v250
	v_sin_f32_e32 v245, v250
	s_nop 1
	v_xor_b32_e32 v245, 0x80000000, v245
	s_nop 0
	v_pk_mul_f32 v[134:135], v[244:245], v[244:245] op_sel:[1,1] op_sel_hi:[1,0]
	s_nop 0
	v_pk_fma_f32 v[246:247], v[244:245], v[244:245], v[134:135] op_sel_hi:[0,1,1] neg_lo:[0,0,1]
	s_nop 0
	v_pk_mul_f32 v[134:135], v[246:247], v[244:245] op_sel:[1,1] op_sel_hi:[1,0]
	s_nop 0
	v_pk_fma_f32 v[248:249], v[246:247], v[244:245], v[134:135] op_sel_hi:[0,1,1] neg_lo:[0,0,1]
	s_nop 0
	v_xor_b32_e32 v245, 0x80000000, v245
	v_xor_b32_e32 v247, 0x80000000, v247
	v_xor_b32_e32 v249, 0x80000000, v249

; DI float2 twid(float r) { return float2{__builtin_amdgcn_cosf(r), -__builtin_amdgcn_sinf(r)}; }
; DI void bfly_inv(float2 s0, float2 s1, float2 s2, float2 s3, float r, float2& o0, float2& o1, float2& o2, float2& o3) {
;   float2 w1 = twid(r), w2 = cmul(w1, w1), w3 = cmul(w2, w1);
;   float2 c0 = s0, c1 = cmulc(s1, w1), c2 = cmulc(s2, w2), c3 = cmulc(s3, w3);
;   const int lq1 = lq2 + 2, Q1 = 1 << lq1, Q2 = 1 << lq2; const float invM1 = 1.f / (float)(4 << lq1), invM2 = 1.f / (float)(4 << lq2);
;   for (int gg = tid; gg < NBT * (N / 16); gg += NTHR) { const int g = gg & (N / 16 - 1); float2* z = z0 + (gg / (N / 16)) * N; const int jp = g & (Q2 - 1), base = ((g >> lq2) << (lq2 + 4)) + jp; float2 x[4][4];
; #pragma unroll
;     for (int q1 = 0; q1 < 4; ++q1)
; #pragma unroll
;       for (int q2 = 0; q2 < 4; ++q2) x[q1][q2] = z[base + q1 * Q1 + q2 * Q2];
; #pragma unroll
;     for (int q1 = 0; q1 < 4; ++q1) bfly_inv(x[q1][0], x[q1][1], x[q1][2], x[q1][3], (float)jp * invM2, x[q1][0], x[q1][1], x[q1][2], x[q1][3]);
; #pragma unroll
;     for (int q2 = 0; q2 < 4; ++q2) bfly_inv(x[0][q2], x[1][q2], x[2][q2], x[3][q2], (float)(jp + q2 * Q2) * invM1, x[0][q2], x[1][q2], x[2][q2], x[3][q2]);
.LBB0_1651:
	s_or_b64 exec, exec, s[14:15]
	s_waitcnt lgkmcnt(0)
	s_barrier
	s_and_saveexec_b64 s[12:13], vcc
	s_cbranch_execz .LBB0_1654
	v_cvt_f32_u32_e32 v11, v79
	v_mul_f32_e32 v8, 0x39800000, v11
	v_sin_f32_e32 v35, v8
	v_cos_f32_e32 v37, v8
	v_mul_f32_e32 v8, v35, v35
	v_fma_f32 v38, v37, v37, -v8
	v_mul_f32_e64 v8, v37, -v35
	v_add_f32_e32 v40, v8, v8
	v_mul_f32_e32 v34, v35, v40
	v_fmac_f32_e32 v34, v37, v38
	v_pk_mov_b32 v[54:55], v[36:37], v[34:35] op_sel:[1,0]
	s_mov_b64 s[0:1], 0
	v_mov_b32_e32 v62, v76
	v_and_b32_e32 v241, 0xff, v62
	v_add_u32_e32 v250, 0x0, v241
	v_cvt_f32_u32_e32 v250, v250
	v_mul_f32_e32 v250, 0x39800000, v250
	v_cos_f32_e32 v218, v250
	v_sin_f32_e32 v219, v250
	s_nop 1
	v_xor_b32_e32 v219, 0x80000000, v219
	s_nop 0
	v_pk_mul_f32 v[128:129], v[218:219], v[218:219] op_sel:[1,1] op_sel_hi:[1,0]
	s_nop 0
	v_pk_fma_f32 v[220:221], v[218:219], v[218:219], v[128:129] op_sel_hi:[0,1,1] neg_lo:[0,0,1]
	s_nop 0
	v_pk_mul_f32 v[128:129], v[220:221], v[218:219] op_sel:[1,1] op_sel_hi:[1,0]
	s_nop 0
	v_pk_fma_f32 v[222:223], v[220:221], v[218:219], v[128:129] op_sel_hi:[0,1,1] neg_lo:[0,0,1]
	s_nop 0
	v_xor_b32_e32 v219, 0x80000000, v219
	v_xor_b32_e32 v221, 0x80000000, v221
	v_xor_b32_e32 v223, 0x80000000, v223
	v_add_u32_e32 v250, 0x100, v241
	v_cvt_f32_u32_e32 v250, v250
	v_mul_f32_e32 v250, 0x39800000, v250
	v_cos_f32_e32 v224, v250
	v_sin_f32_e32 v225, v250
	s_nop 1
	v_xor_b32_e32 v225, 0x80000000, v225
	s_nop 0
	v_pk_mul_f32 v[128:129], v[224:225], v[224:225] op_sel:[1,1] op_sel_hi:[1,0]
	s_nop 0
	v_pk_fma_f32 v[226:227], v[224:225], v[224:225], v[128:129] op_sel_hi:[0,1,1] neg_lo:[0,0,1]
	s_nop 0
	v_pk_mul_f32 v[128:129], v[226:227], v[224:225] op_sel:[1,1] op_sel_hi:[1,0]
	s_nop 0
	v_pk_fma_f32 v[228:229], v[226:227], v[224:225], v[128:129] op_sel_hi:[0,1,1] neg_lo:[0,0,1]
	s_nop 0
	v_xor_b32_e32 v225, 0x80000000, v225
	v_xor_b32_e32 v227, 0x80000000, v227
	v_xor_b32_e32 v229, 0x80000000, v229
	v_add_u32_e32 v250, 0x200, v241
	v_cvt_f32_u32_e32 v250, v250
	v_mul_f32_e32 v250, 0x39800000, v250
	v_cos_f32_e32 v230, v250
	v_sin_f32_e32 v231, v250
	s_nop 1
	v_xor_b32_e32 v231, 0x80000000, v231
	s_nop 0
	v_pk_mul_f32 v[128:129], v[230:231], v[230:231] op_sel:[1,1] op_sel_hi:[1,0]
	s_nop 0
	v_pk_fma_f32 v[232:233], v[230:231], v[230:231], v[128:129] op_sel_hi:[0,1,1] neg_lo:[0,0,1]
	s_nop 0
	v_pk_mul_f32 v[128:129], v[232:233], v[230:231] op_sel:[1,1] op_sel_hi:[1,0]
	s_nop 0
	v_pk_fma_f32 v[234:235], v[232:233], v[230:231], v[128:129] op_sel_hi:[0,1,1] neg_lo:[0,0,1]
	s_nop 0
	v_xor_b32_e32 v231, 0x80000000, v231
	v_xor_b32_e32 v233, 0x80000000, v233
	v_xor_b32_e32 v235, 0x80000000, v235
	v_add_u32_e32 v250, 0x300, v241
	v_cvt_f32_u32_e32 v250, v250
	v_mul_f32_e32 v250, 0x39800000, v250
	v_cos_f32_e32 v236, v250
	v_sin_f32_e32 v237, v250
	s_nop 1
	v_xor_b32_e32 v237, 0x80000000, v237
	s_nop 0
	v_pk_mul_f32 v[128:129], v[236:237], v[236:237] op_sel:[1,1] op_sel_hi:[1,0]
	s_nop 0
	v_pk_fma_f32 v[238:239], v[236:237], v[236:237], v[128:129] op_sel_hi:[0,1,1] neg_lo:[0,0,1]
	s_nop 0
	v_pk_mul_f32 v[128:129], v[238:239], v[236:237] op_sel:[1,1] op_sel_hi:[1,0]
	s_nop 0
	v_pk_fma_f32 v[242:243], v[238:239], v[236:237], v[128:129] op_sel_hi:[0,1,1] neg_lo:[0,0,1]
	s_nop 0
	v_xor_b32_e32 v237, 0x80000000, v237
	v_xor_b32_e32 v239, 0x80000000, v239
	v_xor_b32_e32 v243, 0x80000000, v243
	v_cvt_f32_u32_e32 v250, v241
	v_mul_f32_e32 v250, 0x3a800000, v250
	v_cos_f32_e32 v244, v250
	v_sin_f32_e32 v245, v250
	s_nop 1
	v_xor_b32_e32 v245, 0x80000000, v245
	s_nop 0
	v_pk_mul_f32 v[128:129], v[244:245], v[244:245] op_sel:[1,1] op_sel_hi:[1,0]
	s_nop 0
	v_pk_fma_f32 v[246:247], v[244:245], v[244:245], v[128:129] op_sel_hi:[0,1,1] neg_lo:[0,0,1]
	s_nop 0
	v_pk_mul_f32 v[128:129], v[246:247], v[244:245] op_sel:[1,1] op_sel_hi:[1,0]
	s_nop 0
	v_pk_fma_f32 v[248:249], v[246:247], v[244:245], v[128:129] op_sel_hi:[0,1,1] neg_lo:[0,0,1]
	s_nop 0
	v_xor_b32_e32 v245, 0x80000000, v245
	v_xor_b32_e32 v247, 0x80000000, v247
	v_xor_b32_e32 v249, 0x80000000, v249
